# dil_attn loop: all 8 K frag loads + 7 of 8 V frag loads issued at iteration top, single counted K wait (stacked on v3)
# speedup vs baseline: 1.0140x; 1.0037x over previous
; #define MFMA32(a, b, c) __builtin_amdgcn_mfma_f32_32x32x16_bf16((a), (b), (c), 0, 0, 0)
; DI f32x16 zero16() { f32x16 z; for (int i = 0; i < 16; ++i) z[i] = 0.f; return z; }
; DI void dil_attn_phase(int wv, const bf16_t* qk, const bf16_t* vt, float* oacc, float* stats, bf16_t* ob, int g, int dil) {
;     ...
;         for (int jt = (l0 >= 128) ? 0 : 4 - (l0 >> 5); jt < 5; ++jt) {
;             const int kl0 = l0 - 128 + 32 * jt;
;             const size_t krow = (size_t)b * SEQ + (size_t)(kl0 + prr) * dil + rph;
;             bf16x8 kf[8];
; #pragma unroll
;             for (int ks = 0; ks < 8; ++ks) kf[ks] = *(const bf16x8*)(qk + krow * 2048 + 1024 + head * 128 + ks * 16 + hh * 8);
;             const bf16_t* vb = vt + (size_t)(head * 128 + rr) * M_TOK + (size_t)b * SEQ + (size_t)rph * L + kl0 + 8 * hh;
;             bf16x8 vf[4][2];
; #pragma unroll
;             for (int d = 0; d < 4; ++d)
; #pragma unroll
;                 for (int s = 0; s < 2; ++s) vf[d][s] = *(const bf16x8*)(vb + (size_t)d * 32 * M_TOK + 16 * s);
;             f32x16 S = zero16();
; #pragma unroll
;             for (int ks = 0; ks < 8; ++ks) S = MFMA32(kf[ks], qf[ks], S);
;             float sv[16]; float mx = -INFINITY;
; #pragma unroll
;             for (int i = 0; i < 16; ++i) { const int dist = (l0 + rr) - (kl0 + (i & 7) + 16 * (i >> 3) + 8 * hh); float v = S[i] * c1 - slope2d * (float)dist; v = ((unsigned)dist <= 128u) ? v : -INFINITY; sv[i] = v; mx = fmaxf(mx, v); }
;             mx = fmaxf(mx, __shfl_xor(mx, 32));
.LBB0_281:
	v_ashrrev_i32_e32 v165, 31, v164
	v_mov_b32_e32 v182, v67
	s_ashr_i32 s13, s12, 31
	v_lshlrev_b64 v[66:67], s16, v[164:165]
	s_add_u32 s26, s25, s12
	v_lshl_add_u64 v[66:67], v[66:67], 0, s[4:5]
	s_addc_u32 s27, s10, s13
	v_lshlrev_b64 v[66:67], 12, v[66:67]
	v_lshl_add_u64 v[122:123], s[26:27], 1, v[160:161]
	v_lshl_add_u64 v[124:125], v[162:163], 0, v[66:67]
	global_load_dwordx4 v[130:133], v[122:123], off offset:-256
	global_load_dwordx4 v[126:129], v[122:123], off offset:-224
	global_load_dwordx4 v[66:69], v[124:125], off offset:2048
	global_load_dwordx4 v[114:117], v[124:125], off offset:2080
	global_load_dwordx4 v[118:121], v[124:125], off offset:2112
	global_load_dwordx4 v[200:203], v[124:125], off offset:2144
	global_load_dwordx4 v[204:207], v[124:125], off offset:2176
	global_load_dwordx4 v[208:211], v[124:125], off offset:2208
	global_load_dwordx4 v[212:215], v[124:125], off offset:2240
	global_load_dwordx4 v[184:187], v[124:125], off offset:2272
	s_mov_b32 s2, 0x1ff000
	v_add_co_u32_e32 v134, vcc, s2, v122
	v_add_u32_e32 v170, 23, v181
	s_nop 0
	v_addc_co_u32_e32 v135, vcc, 0, v123, vcc
	s_mov_b32 s2, 0x3ff000
	v_cvt_f32_i32_e32 v167, v170
	v_add_co_u32_e32 v136, vcc, s2, v122
	s_mov_b32 s2, 0x5ff000
	s_nop 0
	v_addc_co_u32_e32 v137, vcc, 0, v123, vcc
	v_add_co_u32_e32 v168, vcc, s2, v122
	v_add_u32_e32 v171, 22, v181
	s_nop 0
	v_addc_co_u32_e32 v169, vcc, 0, v123, vcc
	global_load_dwordx4 v[142:145], v[134:135], off offset:3840
	global_load_dwordx4 v[216:219], v[134:135], off offset:3872
	global_load_dwordx4 v[138:141], v[136:137], off offset:3840
	global_load_dwordx4 v[220:223], v[136:137], off offset:3872
	global_load_dwordx4 v[224:227], v[168:169], off offset:3840
	v_add_u32_e32 v183, 21, v181
	v_cmp_gt_u32_e32 vcc, s69, v170
	v_add_u32_e32 v188, 20, v181
	v_add_u32_e32 v189, 19, v181
	v_add_u32_e32 v190, 18, v181
	v_add_u32_e32 v191, 17, v181
	v_add_u32_e32 v192, 16, v181
	v_add_u32_e32 v193, 7, v181
	v_add_u32_e32 v194, 6, v181
	v_add_u32_e32 v195, 5, v181
	v_add_u32_e32 v196, 4, v181
	v_add_u32_e32 v197, 3, v181
	v_add_u32_e32 v198, 2, v181
	v_add_u32_e32 v199, 1, v181
	s_add_i32 s11, s11, 1
	s_add_i32 s12, s12, 32
	v_add_u32_e32 v164, 32, v164
	s_cmp_gt_i32 s11, 3
	s_waitcnt vmcnt(5)
	v_mfma_f32_32x32x16_bf16 v[66:81], v[66:69], v[82:85], 0
	v_mfma_f32_32x32x16_bf16 v[66:81], v[114:117], v[86:89], v[66:81]
	v_mfma_f32_32x32x16_bf16 v[66:81], v[118:121], v[90:93], v[66:81]
	v_mfma_f32_32x32x16_bf16 v[66:81], v[200:203], v[94:97], v[66:81]
	v_mfma_f32_32x32x16_bf16 v[66:81], v[204:207], v[98:101], v[66:81]
	v_mfma_f32_32x32x16_bf16 v[66:81], v[208:211], v[102:105], v[66:81]
	v_mfma_f32_32x32x16_bf16 v[66:81], v[212:215], v[106:109], v[66:81]
	global_load_dwordx4 v[114:117], v[168:169], off offset:3872
	v_mfma_f32_32x32x16_bf16 v[66:81], v[184:187], v[110:113], v[66:81]
	s_nop 11
	v_mov_b32_e32 v158, v66
	v_pk_mul_f32 v[168:169], v[158:159], v[166:167]
	v_cvt_f32_i32_e32 v167, v171
	v_mov_b32_e32 v158, v67
	v_sub_f32_e32 v66, v168, v169
	v_cndmask_b32_e32 v165, v248, v66, vcc
	v_pk_mul_f32 v[66:67], v[158:159], v[166:167]
	v_cvt_f32_i32_e32 v167, v183
	v_mov_b32_e32 v158, v68
	v_sub_f32_e32 v66, v66, v67
	v_cmp_gt_u32_e32 vcc, s69, v171
	s_nop 1
	v_cndmask_b32_e32 v68, v248, v66, vcc
	v_pk_mul_f32 v[66:67], v[158:159], v[166:167]
	v_cvt_f32_i32_e32 v167, v188
	v_mov_b32_e32 v158, v69
	v_sub_f32_e32 v66, v66, v67
	v_cmp_gt_u32_e32 vcc, s69, v183
	v_max3_f32 v168, v165, s54, v68
	s_nop 0
	v_cndmask_b32_e32 v69, v248, v66, vcc
	v_pk_mul_f32 v[66:67], v[158:159], v[166:167]
	v_cvt_f32_i32_e32 v167, v189
	v_mov_b32_e32 v158, v70
	v_sub_f32_e32 v66, v66, v67
	v_cmp_gt_u32_e32 vcc, s69, v188
	s_nop 1
	v_cndmask_b32_e32 v70, v248, v66, vcc
	v_pk_mul_f32 v[66:67], v[158:159], v[166:167]
	v_cvt_f32_i32_e32 v167, v190
	v_mov_b32_e32 v158, v71
	v_sub_f32_e32 v66, v66, v67
	v_cmp_gt_u32_e32 vcc, s69, v189
	v_max3_f32 v168, v168, v69, v70
	s_nop 0
	v_cndmask_b32_e32 v71, v248, v66, vcc
	v_pk_mul_f32 v[66:67], v[158:159], v[166:167]
	v_cvt_f32_i32_e32 v167, v191
	v_mov_b32_e32 v158, v72
	v_sub_f32_e32 v66, v66, v67
	v_cmp_gt_u32_e32 vcc, s69, v190
	s_nop 1
	v_cndmask_b32_e32 v72, v248, v66, vcc
	v_pk_mul_f32 v[66:67], v[158:159], v[166:167]
	v_cvt_f32_i32_e32 v167, v192
	v_mov_b32_e32 v158, v73
	v_sub_f32_e32 v66, v66, v67
	v_cmp_gt_u32_e32 vcc, s69, v191
	v_max3_f32 v168, v168, v71, v72
	s_nop 0
	v_cndmask_b32_e32 v73, v248, v66, vcc
	v_pk_mul_f32 v[66:67], v[158:159], v[166:167]
	v_cvt_f32_i32_e32 v167, v193
	v_mov_b32_e32 v158, v74
	v_sub_f32_e32 v66, v66, v67
	v_cmp_gt_u32_e32 vcc, s69, v192
	s_nop 1
	v_cndmask_b32_e32 v74, v248, v66, vcc
	v_pk_mul_f32 v[66:67], v[158:159], v[166:167]
	v_cvt_f32_i32_e32 v167, v194
	v_mov_b32_e32 v158, v75
	v_sub_f32_e32 v66, v66, v67
	v_cmp_gt_u32_e32 vcc, s69, v193
	v_max3_f32 v168, v168, v73, v74
	s_nop 0
	v_cndmask_b32_e32 v75, v248, v66, vcc
	v_pk_mul_f32 v[66:67], v[158:159], v[166:167]
	v_cvt_f32_i32_e32 v167, v195
	v_mov_b32_e32 v158, v76
	v_sub_f32_e32 v66, v66, v67
	v_cmp_gt_u32_e32 vcc, s69, v194
	s_nop 1
	v_cndmask_b32_e32 v76, v248, v66, vcc
	v_pk_mul_f32 v[66:67], v[158:159], v[166:167]
	v_cvt_f32_i32_e32 v167, v196
	v_mov_b32_e32 v158, v77
	v_sub_f32_e32 v66, v66, v67
	v_cmp_gt_u32_e32 vcc, s69, v195
	v_max3_f32 v168, v168, v75, v76
	s_nop 0
	v_cndmask_b32_e32 v77, v248, v66, vcc
	v_pk_mul_f32 v[66:67], v[158:159], v[166:167]
	v_cvt_f32_i32_e32 v167, v197
	v_mov_b32_e32 v158, v78
	v_sub_f32_e32 v66, v66, v67
	v_cmp_gt_u32_e32 vcc, s69, v196
	s_nop 1
	v_cndmask_b32_e32 v78, v248, v66, vcc
	v_pk_mul_f32 v[66:67], v[158:159], v[166:167]
	v_cvt_f32_i32_e32 v167, v198
	v_mov_b32_e32 v158, v79
	v_sub_f32_e32 v66, v66, v67
	v_cmp_gt_u32_e32 vcc, s69, v197
	v_max3_f32 v168, v168, v77, v78
	s_nop 0
	v_cndmask_b32_e32 v79, v248, v66, vcc
	v_pk_mul_f32 v[66:67], v[158:159], v[166:167]
	v_cvt_f32_i32_e32 v167, v199
	v_mov_b32_e32 v158, v80
	v_sub_f32_e32 v66, v66, v67
	v_cmp_gt_u32_e32 vcc, s69, v198
	s_nop 1
	v_cndmask_b32_e32 v80, v248, v66, vcc
	v_pk_mul_f32 v[66:67], v[158:159], v[166:167]
	v_cvt_f32_i32_e32 v167, v181
	v_mov_b32_e32 v158, v81
	v_sub_f32_e32 v66, v66, v67
	v_cmp_gt_u32_e32 vcc, s69, v199
	v_max3_f32 v168, v168, v79, v80
	s_nop 0
	v_cndmask_b32_e32 v81, v248, v66, vcc
	v_pk_mul_f32 v[66:67], v[158:159], v[166:167]
	v_cmp_gt_u32_e32 vcc, s69, v181
	v_sub_f32_e32 v66, v66, v67
	v_subrev_u32_e32 v181, 32, v181
	v_cndmask_b32_e32 v66, v248, v66, vcc
	v_max3_f32 v67, v168, v81, v66
	ds_bpermute_b32 v158, v238, v67
	s_waitcnt lgkmcnt(0)
; DI float fexp2(float x) { return __builtin_amdgcn_exp2f(x); }
; #define MFMA32(a, b, c) __builtin_amdgcn_mfma_f32_32x32x16_bf16((a), (b), (c), 0, 0, 0)
; DI void dil_attn_phase(int wv, const bf16_t* qk, const bf16_t* vt, float* oacc, float* stats, bf16_t* ob, int g, int dil) {
;     ...
;             mx = fmaxf(mx, __shfl_xor(mx, 32));
;             const float mn = fmaxf(m, mx), alpha = fexp2(m - mn); m = mn;
;             float ps = 0.f; f32x16 P;
; #pragma unroll
;             for (int i = 0; i < 16; ++i) { const float pv = fexp2(sv[i] - mn); P[i] = pv; ps += pv; }
;             l = l * alpha + ps;
; #pragma unroll
;             for (int d = 0; d < 4; ++d) O[d] = O[d] * alpha;
;             const bf16x8 pf0 = pack8(P, 0), pf1 = pack8(P, 1);
; #pragma unroll
;             for (int d = 0; d < 4; ++d) { O[d] = MFMA32(vf[d][0], pf0, O[d]); O[d] = MFMA32(vf[d][1], pf1, O[d]); }
	v_max3_f32 v67, v182, v67, v158
	v_sub_f32_e32 v158, v182, v67
	v_sub_f32_e32 v165, v165, v67
	v_sub_f32_e32 v68, v68, v67
	v_sub_f32_e32 v69, v69, v67
	v_sub_f32_e32 v70, v70, v67
	v_sub_f32_e32 v71, v71, v67
	v_sub_f32_e32 v72, v72, v67
	v_sub_f32_e32 v73, v73, v67
	v_sub_f32_e32 v74, v74, v67
	v_sub_f32_e32 v167, v66, v67
	v_exp_f32_e32 v165, v165
	v_exp_f32_e32 v168, v68
	v_exp_f32_e32 v169, v69
	v_exp_f32_e32 v170, v70
	v_exp_f32_e32 v171, v71
	v_exp_f32_e32 v72, v72
	v_exp_f32_e32 v73, v73
	v_exp_f32_e32 v74, v74
	v_exp_f32_e32 v66, v158
	v_cvt_pk_bf16_f32 v68, v165, v168
	v_cvt_pk_bf16_f32 v69, v169, v170
	v_cvt_pk_bf16_f32 v70, v171, v72
	v_pk_mul_f32 v[48:49], v[48:49], v[66:67] op_sel_hi:[1,0]
	v_pk_mul_f32 v[46:47], v[46:47], v[66:67] op_sel_hi:[1,0]
	v_pk_mul_f32 v[44:45], v[44:45], v[66:67] op_sel_hi:[1,0]
	v_cvt_pk_bf16_f32 v71, v73, v74
	v_pk_mul_f32 v[42:43], v[42:43], v[66:67] op_sel_hi:[1,0]
	v_pk_mul_f32 v[40:41], v[40:41], v[66:67] op_sel_hi:[1,0]
	v_pk_mul_f32 v[38:39], v[38:39], v[66:67] op_sel_hi:[1,0]
	v_pk_mul_f32 v[36:37], v[36:37], v[66:67] op_sel_hi:[1,0]
	v_pk_mul_f32 v[34:35], v[34:35], v[66:67] op_sel_hi:[1,0]
	v_sub_f32_e32 v75, v75, v67
	v_sub_f32_e32 v76, v76, v67
	s_waitcnt vmcnt(5)
	v_mfma_f32_32x32x16_bf16 v[34:49], v[142:145], v[68:71], v[34:49]
	v_sub_f32_e32 v77, v77, v67
	v_sub_f32_e32 v78, v78, v67
	v_sub_f32_e32 v79, v79, v67
	v_sub_f32_e32 v80, v80, v67
	v_sub_f32_e32 v81, v81, v67
	v_pk_mul_f32 v[64:65], v[64:65], v[66:67] op_sel_hi:[1,0]
	v_pk_mul_f32 v[62:63], v[62:63], v[66:67] op_sel_hi:[1,0]
	v_pk_mul_f32 v[60:61], v[60:61], v[66:67] op_sel_hi:[1,0]
	v_pk_mul_f32 v[58:59], v[58:59], v[66:67] op_sel_hi:[1,0]
	v_pk_mul_f32 v[56:57], v[56:57], v[66:67] op_sel_hi:[1,0]
	v_pk_mul_f32 v[54:55], v[54:55], v[66:67] op_sel_hi:[1,0]
	v_pk_mul_f32 v[52:53], v[52:53], v[66:67] op_sel_hi:[1,0]
	v_pk_mul_f32 v[50:51], v[50:51], v[66:67] op_sel_hi:[1,0]
	v_pk_mul_f32 v[32:33], v[32:33], v[66:67] op_sel_hi:[1,0]
	v_pk_mul_f32 v[30:31], v[30:31], v[66:67] op_sel_hi:[1,0]
	v_pk_mul_f32 v[28:29], v[28:29], v[66:67] op_sel_hi:[1,0]
	v_pk_mul_f32 v[26:27], v[26:27], v[66:67] op_sel_hi:[1,0]
	v_pk_mul_f32 v[24:25], v[24:25], v[66:67] op_sel_hi:[1,0]
	v_pk_mul_f32 v[22:23], v[22:23], v[66:67] op_sel_hi:[1,0]
	v_pk_mul_f32 v[20:21], v[20:21], v[66:67] op_sel_hi:[1,0]
	v_pk_mul_f32 v[18:19], v[18:19], v[66:67] op_sel_hi:[1,0]
	v_exp_f32_e32 v75, v75
	v_exp_f32_e32 v76, v76
	v_exp_f32_e32 v77, v77
	v_exp_f32_e32 v78, v78
	v_exp_f32_e32 v79, v79
	v_mfma_f32_32x32x16_bf16 v[50:65], v[130:133], v[68:71], v[50:65]
	v_exp_f32_e32 v80, v80
	v_exp_f32_e32 v81, v81
	v_exp_f32_e32 v130, v167
	v_pk_mul_f32 v[16:17], v[16:17], v[66:67] op_sel_hi:[1,0]
	v_pk_mul_f32 v[14:15], v[14:15], v[66:67] op_sel_hi:[1,0]
	v_pk_mul_f32 v[12:13], v[12:13], v[66:67] op_sel_hi:[1,0]
	v_pk_mul_f32 v[10:11], v[10:11], v[66:67] op_sel_hi:[1,0]
	s_waitcnt vmcnt(3)
	v_mfma_f32_32x32x16_bf16 v[18:33], v[138:141], v[68:71], v[18:33]
	v_mul_f32_e64 v8, v8, v66
	v_mul_f32_e64 v9, v9, v66
	v_mul_f32_e64 v6, v6, v66
	v_mul_f32_e64 v7, v7, v66
	v_mul_f32_e64 v4, v4, v66
	v_mul_f32_e64 v5, v5, v66
	v_pk_mul_f32 v[2:3], v[2:3], v[66:67] op_sel_hi:[1,0]
	s_waitcnt vmcnt(1)
	s_nop 0
	v_mfma_f32_32x32x16_bf16 v[2:17], v[224:227], v[68:71], v[2:17]
	v_cvt_pk_bf16_f32 v68, v75, v76
	v_cvt_pk_bf16_f32 v69, v77, v78
	v_cvt_pk_bf16_f32 v70, v79, v80
	v_cvt_pk_bf16_f32 v71, v81, v130
	s_nop 1
	v_mfma_f32_32x32x16_bf16 v[34:49], v[216:219], v[68:71], v[34:49]
	v_add_f32_e32 v122, 0, v165
	v_add_f32_e32 v122, v168, v122
	v_add_f32_e32 v122, v169, v122
	v_mfma_f32_32x32x16_bf16 v[18:33], v[220:223], v[68:71], v[18:33]
	v_add_f32_e32 v118, v170, v122
	v_add_f32_e32 v118, v171, v118
	v_add_f32_e32 v72, v72, v118
	v_add_f32_e32 v72, v73, v72
	v_add_f32_e32 v72, v74, v72
	v_add_f32_e32 v72, v75, v72
	v_add_f32_e32 v72, v76, v72
	v_mfma_f32_32x32x16_bf16 v[50:65], v[126:129], v[68:71], v[50:65]
	v_mov_b32_e32 v126, v180
	s_waitcnt vmcnt(0)
	v_mfma_f32_32x32x16_bf16 v[2:17], v[114:117], v[68:71], v[2:17]
	v_add_f32_e32 v68, v77, v72
	v_add_f32_e32 v68, v78, v68
	v_add_f32_e32 v68, v79, v68
	v_add_f32_e32 v68, v80, v68
	v_add_f32_e32 v68, v81, v68
	v_add_f32_e32 v180, v130, v68
	v_fmac_f32_e32 v180, v126, v66
	s_cbranch_scc0 .LBB0_281
